# prologue weight copies: the per-row RMSNorm-gain loads no longer serialise the item's eight row loads (gains into own registers, one wait and the scaling moved to the LDS write-out)
# speedup vs baseline: 1.0050x; 1.0050x over previous
; #define LAS __attribute__((address_space(3)))
; __device__ __forceinline__ TItem titem(const Args& a, int it) {
;     ...
;     const int nblk = t.N / 256; t.k0 = 64 * (r / nblk); t.n0 = 256 * (r % nblk);
;     return t;
; }
; __device__ __forceinline__ void prologue(const Args& a, LAS unsigned char* lds, int tid, int wave, int lane) {
;     unsigned char* ws = a.ws;
;     const int gw = blockIdx.x * 8 + wave, NGW = gridDim.x * 8;
;     {   constexpr int TS = 257; LAS float* tile = (LAS float*)lds;
;         f32x4 v[8]; int it = blockIdx.x;
;         if (it < T_ITEMS) { const TItem t = titem(a, it);
; #pragma unroll
;             for (int i = 0; i < 8; ++i) { v[i] = __builtin_nontemporal_load((const f32x4*)(t.W + (size_t)(t.k0 + 8 * wave + i) * t.N + t.n0 + 4 * lane)); if (t.gain) v[i] = v[i] * t.gain[t.k0 + 8 * wave + i]; } }
.LBB0_47:
	s_lshr_b32 s16, s3, 8
	v_cvt_f32_i32_e32 v0, s16
	s_sext_i32_i16 s0, s23
	v_cvt_f32_i32_e32 v1, s0
	s_ashr_i32 s0, s0, 30
	v_rcp_iflag_f32_e32 v2, v0
	s_or_b32 s17, s0, 1
	v_lshlrev_b32_e32 v4, 4, v32
	v_mov_b32_e32 v5, 0
	v_mul_f32_e32 v2, v1, v2
	v_trunc_f32_e32 v2, v2
	v_fma_f32 v1, -v2, v0, v1
	v_cvt_i32_f32_e32 v2, v2
	v_cmp_ge_f32_e64 s[0:1], |v1|, v0
	s_and_b64 s[0:1], s[0:1], exec
	s_cselect_b32 s0, s17, 0
	v_readfirstlane_b32 s1, v2
	s_add_i32 s0, s1, s0
	s_sext_i32_i16 s1, s0
	s_mul_i32 s0, s0, s16
	s_sub_i32 s0, s23, s0
	s_sext_i32_i16 s0, s0
	s_lshl_b32 s1, s1, 6
	s_lshl_b32 s0, s0, 8
	s_lshl_b32 s16, s94, 3
	s_add_i32 s16, s1, s16
	s_ashr_i32 s1, s0, 31
	s_lshl_b64 s[0:1], s[0:1], 2
	s_add_u32 s0, s18, s0
	s_addc_u32 s1, s19, s1
	s_cmp_lg_u64 s[14:15], 0
	s_cselect_b64 s[18:19], -1, 0
	s_ashr_i32 s17, s16, 31
	v_lshl_add_u64 v[28:29], s[0:1], 0, v[4:5]
	s_mul_i32 s0, s17, s3
	s_mul_hi_u32 s1, s16, s3
	s_add_i32 s1, s1, s0
	s_mul_i32 s0, s16, s3
	v_lshl_add_u64 v[0:1], s[0:1], 2, v[28:29]
	s_mov_b32 s98, 0
	global_load_dwordx4 v[0:3], v[0:1], off nt
	s_cmp_eq_u64 s[14:15], 0
	s_cbranch_scc1 .LBB0_49
	s_lshl_b64 s[0:1], s[16:17], 2
	s_add_u32 s0, s14, s0
	s_addc_u32 s1, s15, s1
	s_mov_b32 s98, 1
	global_load_dword v70, v5, s[0:1]
.LBB0_49:
	s_or_b32 s0, s16, 1
	s_mul_i32 s20, s17, s3
	s_mul_hi_u32 s1, s0, s3
	s_add_i32 s1, s1, s20
	s_mul_i32 s0, s0, s3
	v_lshl_add_u64 v[4:5], s[0:1], 2, v[28:29]
	global_load_dwordx4 v[4:7], v[4:5], off nt
	v_cndmask_b32_e64 v8, 0, 1, s[18:19]
	v_cmp_ne_u32_e64 s[0:1], 1, v8
	s_andn2_b64 vcc, exec, s[18:19]
	s_cbranch_vccnz .LBB0_51
	s_lshl_b64 s[18:19], s[16:17], 2
	s_add_u32 s18, s14, s18
	s_addc_u32 s19, s15, s19
	v_mov_b32_e32 v8, 0
	global_load_dword v72, v8, s[18:19] offset:4
.LBB0_51:
	s_or_b32 s18, s16, 2
	s_mul_hi_u32 s19, s18, s3
	s_add_i32 s19, s19, s20
	s_mul_i32 s18, s18, s3
	v_lshl_add_u64 v[8:9], s[18:19], 2, v[28:29]
	global_load_dwordx4 v[8:11], v[8:9], off nt
	s_and_b64 vcc, exec, s[0:1]
	s_cbranch_vccnz .LBB0_53
	s_lshl_b64 s[18:19], s[16:17], 2
	s_add_u32 s18, s14, s18
	s_addc_u32 s19, s15, s19
	v_mov_b32_e32 v12, 0
	global_load_dword v74, v12, s[18:19] offset:8
.LBB0_53:
	s_or_b32 s18, s16, 3
	s_mul_hi_u32 s19, s18, s3
	s_add_i32 s19, s19, s20
	s_mul_i32 s18, s18, s3
	v_lshl_add_u64 v[12:13], s[18:19], 2, v[28:29]
	global_load_dwordx4 v[12:15], v[12:13], off nt
	s_and_b64 vcc, exec, s[0:1]
	s_cbranch_vccnz .LBB0_55
	s_lshl_b64 s[18:19], s[16:17], 2
	s_add_u32 s18, s14, s18
	s_addc_u32 s19, s15, s19
	v_mov_b32_e32 v16, 0
	global_load_dword v76, v16, s[18:19] offset:12
.LBB0_55:
	s_or_b32 s18, s16, 4
	s_mul_hi_u32 s19, s18, s3
	s_add_i32 s19, s19, s20
	s_mul_i32 s18, s18, s3
	v_lshl_add_u64 v[16:17], s[18:19], 2, v[28:29]
	global_load_dwordx4 v[16:19], v[16:17], off nt
	s_and_b64 vcc, exec, s[0:1]
	s_cbranch_vccnz .LBB0_57
	s_lshl_b64 s[18:19], s[16:17], 2
	s_add_u32 s18, s14, s18
	s_addc_u32 s19, s15, s19
	v_mov_b32_e32 v20, 0
	global_load_dword v78, v20, s[18:19] offset:16
.LBB0_57:
	s_or_b32 s18, s16, 5
	s_mul_hi_u32 s19, s18, s3
	s_add_i32 s19, s19, s20
	s_mul_i32 s18, s18, s3
	v_lshl_add_u64 v[20:21], s[18:19], 2, v[28:29]
	global_load_dwordx4 v[20:23], v[20:21], off nt
	s_and_b64 vcc, exec, s[0:1]
	s_cbranch_vccnz .LBB0_59
	s_lshl_b64 s[18:19], s[16:17], 2
	s_add_u32 s18, s14, s18
	s_addc_u32 s19, s15, s19
	v_mov_b32_e32 v24, 0
	global_load_dword v80, v24, s[18:19] offset:20
.LBB0_59:
	s_or_b32 s18, s16, 6
	s_mul_hi_u32 s19, s18, s3
	s_add_i32 s19, s19, s20
	s_mul_i32 s18, s18, s3
	v_lshl_add_u64 v[24:25], s[18:19], 2, v[28:29]
	global_load_dwordx4 v[24:27], v[24:25], off nt
	s_and_b64 vcc, exec, s[0:1]
	s_cbranch_vccnz .LBB0_61
	s_lshl_b64 s[18:19], s[16:17], 2
	s_add_u32 s18, s14, s18
	s_addc_u32 s19, s15, s19
	v_mov_b32_e32 v30, 0
	global_load_dword v82, v30, s[18:19] offset:24
.LBB0_61:
	s_or_b32 s18, s16, 7
	s_mul_hi_u32 s19, s18, s3
	s_add_i32 s19, s19, s20
	s_mul_i32 s18, s18, s3
	v_lshl_add_u64 v[28:29], s[18:19], 2, v[28:29]
	global_load_dwordx4 v[28:31], v[28:29], off nt
	s_and_b64 vcc, exec, s[0:1]
	s_cbranch_vccnz .LBB0_63
	s_lshl_b64 s[0:1], s[16:17], 2
	s_add_u32 s0, s14, s0
	s_addc_u32 s1, s15, s1
	v_mov_b32_e32 v34, 0
	global_load_dword v84, v34, s[0:1] offset:28

; __device__ __forceinline__ TItem titem(const Args& a, int it) {
;     constexpr int I0 = (DM / 64) * (INC / 256), I1 = (512 / 64) * (512 / 256), I2 = (512 / 64) * (1024 / 256), I3 = I2, I4 = (DM / 64) * (DM / 256), I5 = (DM / 64) * (FF / 256), I6 = (FF / 64) * (DM / 256);
;     constexpr int IL = I0 + I1 + I2 + I3 + I4 + I5 + I6;
;     const int l = it / IL; int r = it % IL; bf16_t* Wl = (bf16_t*)(a.ws + WS_W) + (size_t)l * W_LAYER; TItem t;
;     if (r < I0) { t.W = a.in[I_WIN] + (size_t)l * DM * INC; t.gain = a.in[I_N1G] + l * DM; t.WT = Wl + W_IN; t.K = DM; t.N = INC; }
;     else if ((r -= I0) < I1) { t.W = a.in[I_WGLU] + (size_t)l * 512 * 512; t.gain = nullptr; t.WT = Wl + W_GLU; t.K = 512; t.N = 512; }
;     else if ((r -= I1) < I2) { t.W = a.in[I_WAO] + (size_t)l * 512 * 1024; t.gain = nullptr; t.WT = Wl + W_AO; t.K = 512; t.N = 1024; }
;     else if ((r -= I2) < I3) { t.W = a.in[I_WSO] + (size_t)l * 512 * 1024; t.gain = nullptr; t.WT = Wl + W_SO; t.K = 512; t.N = 1024; }
;     else if ((r -= I3) < I4) { t.W = a.in[I_WOUT] + (size_t)l * DM * DM; t.gain = nullptr; t.WT = Wl + W_OUT; t.K = DM; t.N = DM; }
;     else if ((r -= I4) < I5) { t.W = a.in[I_WUP] + (size_t)l * DM * FF; t.gain = a.in[I_N2G] + l * DM; t.WT = Wl + W_UP; t.K = DM; t.N = FF; }
;     else { r -= I5; t.W = a.in[I_WDN] + (size_t)l * FF * DM; t.gain = nullptr; t.WT = Wl + W_DN; t.K = FF; t.N = DM; }
;     const int nblk = t.N / 256; t.k0 = 64 * (r / nblk); t.n0 = 256 * (r % nblk);
;     return t;
; }
; __device__ __forceinline__ void prologue(const Args& a, LAS unsigned char* lds, int tid, int wave, int lane) {
;     unsigned char* ws = a.ws;
;     const int gw = blockIdx.x * 8 + wave, NGW = gridDim.x * 8;
;     {   constexpr int TS = 257; LAS float* tile = (LAS float*)lds;
;         f32x4 v[8]; int it = blockIdx.x;
;         if (it < T_ITEMS) { const TItem t = titem(a, it);
; #pragma unroll
;             for (int i = 0; i < 8; ++i) { v[i] = __builtin_nontemporal_load((const f32x4*)(t.W + (size_t)(t.k0 + 8 * wave + i) * t.N + t.n0 + 4 * lane)); if (t.gain) v[i] = v[i] * t.gain[t.k0 + 8 * wave + i]; } }
;         for (; it < T_ITEMS; it += gridDim.x) {
;             const TItem t = titem(a, it);
; #pragma unroll
;             for (int i = 0; i < 8; ++i) { LAS float* tp = tile + (8 * wave + i) * TS + 4 * lane; tp[0] = v[i][0]; tp[1] = v[i][1]; tp[2] = v[i][2]; tp[3] = v[i][3]; }
.LBB0_88:
	s_add_i32 s28, s28, s34
	s_cmpk_gt_i32 s28, 0x6bf
	s_cselect_b64 s[16:17], -1, 0
	s_and_b64 vcc, exec, s[16:17]
	s_cmp_eq_u32 s98, 0
	s_cbranch_scc1 .Lwt_nogain
	s_waitcnt vmcnt(0)
	v_pk_mul_f32 v[2:3], v[2:3], v[70:71] op_sel_hi:[1,0]
	v_pk_mul_f32 v[0:1], v[0:1], v[70:71] op_sel_hi:[1,0]
	v_pk_mul_f32 v[6:7], v[6:7], v[72:73] op_sel_hi:[1,0]
	v_pk_mul_f32 v[4:5], v[4:5], v[72:73] op_sel_hi:[1,0]
	v_pk_mul_f32 v[10:11], v[10:11], v[74:75] op_sel_hi:[1,0]
	v_pk_mul_f32 v[8:9], v[8:9], v[74:75] op_sel_hi:[1,0]
	v_pk_mul_f32 v[14:15], v[14:15], v[76:77] op_sel_hi:[1,0]
	v_pk_mul_f32 v[12:13], v[12:13], v[76:77] op_sel_hi:[1,0]
	v_pk_mul_f32 v[18:19], v[18:19], v[78:79] op_sel_hi:[1,0]
	v_pk_mul_f32 v[16:17], v[16:17], v[78:79] op_sel_hi:[1,0]
	v_pk_mul_f32 v[22:23], v[22:23], v[80:81] op_sel_hi:[1,0]
	v_pk_mul_f32 v[20:21], v[20:21], v[80:81] op_sel_hi:[1,0]
	v_pk_mul_f32 v[26:27], v[26:27], v[82:83] op_sel_hi:[1,0]
	v_pk_mul_f32 v[24:25], v[24:25], v[82:83] op_sel_hi:[1,0]
	v_pk_mul_f32 v[30:31], v[30:31], v[84:85] op_sel_hi:[1,0]
	v_pk_mul_f32 v[28:29], v[28:29], v[84:85] op_sel_hi:[1,0]
.Lwt_nogain:
	s_waitcnt vmcnt(7)
	ds_write_b128 v46, v[0:3]
	s_waitcnt vmcnt(6)
	ds_write2_b32 v47, v4, v5 offset1:1
	ds_write2_b32 v48, v6, v7 offset1:1
	s_waitcnt vmcnt(5)
	ds_write2_b64 v49, v[8:9], v[10:11] offset1:1
	s_waitcnt vmcnt(4)
	ds_write2_b32 v50, v12, v13 offset1:1
	ds_write2_b32 v51, v14, v15 offset1:1
	s_waitcnt vmcnt(3)
	ds_write_b128 v46, v[16:19] offset:4112
	s_waitcnt vmcnt(2)
	ds_write2_b32 v52, v20, v21 offset1:1
	ds_write2_b32 v53, v22, v23 offset1:1
	s_waitcnt vmcnt(1)
	ds_write2_b64 v54, v[24:25], v[26:27] offset1:1
	s_waitcnt vmcnt(0)
	ds_write2_b32 v55, v28, v29 offset1:1
	ds_write2_b32 v56, v30, v31 offset1:1
	s_waitcnt lgkmcnt(0)
	s_barrier
	s_cbranch_vccnz .LBB0_65
	s_mul_hi_i32 s0, s28, 0x4bda12f7
	s_lshr_b32 s1, s0, 31
	s_ashr_i32 s0, s0, 8
	s_add_i32 s0, s0, s1
	s_mul_i32 s1, s0, 0xfffffca0
	s_add_i32 s33, s28, s1
	s_ashr_i32 s1, s0, 31
	s_cmpk_gt_i32 s33, 0xcf
	s_mov_b64 s[20:21], -1
	s_cbranch_scc0 .LBB0_110
	s_mul_i32 s18, s0, 0x360
	s_sub_i32 s53, s28, s18
	s_cmpk_gt_u32 s33, 0xdf
	s_cbranch_scc0 .LBB0_107
	s_cmpk_gt_u32 s33, 0xff
	s_cbranch_scc0 .LBB0_104
	s_cmpk_gt_u32 s33, 0x11f
	s_cbranch_scc0 .LBB0_101
	s_cmpk_gt_u32 s33, 0x15f
	s_cbranch_scc0 .LBB0_98
	s_lshl_b64 s[24:25], s[0:1], 24
	s_cmpk_gt_u32 s33, 0x25f
	s_mov_b64 s[18:19], -1
	s_cbranch_scc0 .LBB0_96
	s_add_i32 s52, s53, 0xfffffda0
	s_add_u32 s22, s10, s24
	s_addc_u32 s23, s11, s25
	s_mov_b64 s[18:19], 0

; #define LAS __attribute__((address_space(3)))
; __device__ __forceinline__ TItem titem(const Args& a, int it) {
;     ...
;     const int nblk = t.N / 256; t.k0 = 64 * (r / nblk); t.n0 = 256 * (r % nblk);
;     return t;
; }
; __device__ __forceinline__ void prologue(const Args& a, LAS unsigned char* lds, int tid, int wave, int lane) {
;     unsigned char* ws = a.ws;
;     const int gw = blockIdx.x * 8 + wave, NGW = gridDim.x * 8;
;     {   constexpr int TS = 257; LAS float* tile = (LAS float*)lds;
;         f32x4 v[8]; int it = blockIdx.x;
;         if (it < T_ITEMS) { const TItem t = titem(a, it);
; #pragma unroll
;             for (int i = 0; i < 8; ++i) { v[i] = __builtin_nontemporal_load((const f32x4*)(t.W + (size_t)(t.k0 + 8 * wave + i) * t.N + t.n0 + 4 * lane)); if (t.gain) v[i] = v[i] * t.gain[t.k0 + 8 * wave + i]; } }
;         for (; it < T_ITEMS; it += gridDim.x) {
;             const TItem t = titem(a, it);
; #pragma unroll
;             for (int i = 0; i < 8; ++i) { LAS float* tp = tile + (8 * wave + i) * TS + 4 * lane; tp[0] = v[i][0]; tp[1] = v[i][1]; tp[2] = v[i][2]; tp[3] = v[i][3]; }
;             __syncthreads();
;             if (it + (int)gridDim.x < T_ITEMS) { const TItem tn = titem(a, it + gridDim.x);
; #pragma unroll
;                 for (int i = 0; i < 8; ++i) { v[i] = __builtin_nontemporal_load((const f32x4*)(tn.W + (size_t)(tn.k0 + 8 * wave + i) * tn.N + tn.n0 + 4 * lane)); if (tn.gain) v[i] = v[i] * tn.gain[tn.k0 + 8 * wave + i]; } }
.LBB0_112:
	s_lshr_b32 s20, s31, 8
	v_cvt_f32_i32_e32 v0, s20
	s_sext_i32_i16 s0, s52
	v_cvt_f32_i32_e32 v1, s0
	s_ashr_i32 s0, s0, 30
	v_rcp_iflag_f32_e32 v2, v0
	s_or_b32 s21, s0, 1
	v_mul_f32_e32 v2, v1, v2
	v_trunc_f32_e32 v2, v2
	v_fma_f32 v1, -v2, v0, v1
	v_cvt_i32_f32_e32 v2, v2
	v_cmp_ge_f32_e64 s[0:1], |v1|, v0
	s_and_b64 s[0:1], s[0:1], exec
	s_cselect_b32 s0, s21, 0
	v_readfirstlane_b32 s1, v2
	s_add_i32 s0, s1, s0
	s_sext_i32_i16 s1, s0
	s_mul_i32 s0, s0, s20
	s_sub_i32 s0, s52, s0
	s_sext_i32_i16 s0, s0
	s_lshl_b32 s1, s1, 6
	s_lshl_b32 s0, s0, 8
	s_add_i32 s20, s1, s3
	s_ashr_i32 s1, s0, 31
	s_lshl_b64 s[0:1], s[0:1], 2
	s_add_u32 s0, s22, s0
	s_addc_u32 s1, s23, s1
	s_cmp_lg_u64 s[18:19], 0
	s_cselect_b64 s[22:23], -1, 0
	s_ashr_i32 s21, s20, 31
	v_lshl_add_u64 v[28:29], s[0:1], 0, v[34:35]
	s_mul_i32 s0, s21, s31
	s_mul_hi_u32 s1, s20, s31
	s_add_i32 s1, s1, s0
	s_mul_i32 s0, s20, s31
	v_lshl_add_u64 v[0:1], s[0:1], 2, v[28:29]
	s_mov_b32 s98, 0
	global_load_dwordx4 v[0:3], v[0:1], off nt
	s_cmp_eq_u64 s[18:19], 0
	s_cbranch_scc1 .LBB0_114
	s_lshl_b64 s[0:1], s[20:21], 2
	s_add_u32 s0, s18, s0
	s_addc_u32 s1, s19, s1
	s_mov_b32 s98, 1
	global_load_dword v70, v35, s[0:1]
.LBB0_114:
	s_or_b32 s0, s20, 1
	s_mul_i32 s24, s21, s31
	s_mul_hi_u32 s1, s0, s31
	s_add_i32 s1, s1, s24
	s_mul_i32 s0, s0, s31
	v_lshl_add_u64 v[4:5], s[0:1], 2, v[28:29]
	global_load_dwordx4 v[4:7], v[4:5], off nt
	v_cndmask_b32_e64 v8, 0, 1, s[22:23]
	v_cmp_ne_u32_e64 s[0:1], 1, v8
	s_andn2_b64 vcc, exec, s[22:23]
	s_cbranch_vccnz .LBB0_116
	s_lshl_b64 s[22:23], s[20:21], 2
	s_add_u32 s22, s18, s22
	s_addc_u32 s23, s19, s23
	global_load_dword v72, v35, s[22:23] offset:4
.LBB0_116:
	s_or_b32 s22, s20, 2
	s_mul_hi_u32 s23, s22, s31
	s_add_i32 s23, s23, s24
	s_mul_i32 s22, s22, s31
	v_lshl_add_u64 v[8:9], s[22:23], 2, v[28:29]
	global_load_dwordx4 v[8:11], v[8:9], off nt
	s_and_b64 vcc, exec, s[0:1]
	s_cbranch_vccnz .LBB0_118
	s_lshl_b64 s[22:23], s[20:21], 2
	s_add_u32 s22, s18, s22
	s_addc_u32 s23, s19, s23
	global_load_dword v74, v35, s[22:23] offset:8
.LBB0_118:
	s_or_b32 s22, s20, 3
	s_mul_hi_u32 s23, s22, s31
	s_add_i32 s23, s23, s24
	s_mul_i32 s22, s22, s31
	v_lshl_add_u64 v[12:13], s[22:23], 2, v[28:29]
	global_load_dwordx4 v[12:15], v[12:13], off nt
	s_and_b64 vcc, exec, s[0:1]
	s_cbranch_vccnz .LBB0_120
	s_lshl_b64 s[22:23], s[20:21], 2
	s_add_u32 s22, s18, s22
	s_addc_u32 s23, s19, s23
	global_load_dword v76, v35, s[22:23] offset:12
.LBB0_120:
	s_or_b32 s22, s20, 4
	s_mul_hi_u32 s23, s22, s31
	s_add_i32 s23, s23, s24
	s_mul_i32 s22, s22, s31
	v_lshl_add_u64 v[16:17], s[22:23], 2, v[28:29]
	global_load_dwordx4 v[16:19], v[16:17], off nt
	s_and_b64 vcc, exec, s[0:1]
	s_cbranch_vccnz .LBB0_122
	s_lshl_b64 s[22:23], s[20:21], 2
	s_add_u32 s22, s18, s22
	s_addc_u32 s23, s19, s23
	global_load_dword v78, v35, s[22:23] offset:16
.LBB0_122:
	s_or_b32 s22, s20, 5
	s_mul_hi_u32 s23, s22, s31
	s_add_i32 s23, s23, s24
	s_mul_i32 s22, s22, s31
	v_lshl_add_u64 v[20:21], s[22:23], 2, v[28:29]
	global_load_dwordx4 v[20:23], v[20:21], off nt
	s_and_b64 vcc, exec, s[0:1]
	s_cbranch_vccnz .LBB0_124
	s_lshl_b64 s[22:23], s[20:21], 2
	s_add_u32 s22, s18, s22
	s_addc_u32 s23, s19, s23
	global_load_dword v80, v35, s[22:23] offset:20
.LBB0_124:
	s_or_b32 s22, s20, 6
	s_mul_hi_u32 s23, s22, s31
	s_add_i32 s23, s23, s24
	s_mul_i32 s22, s22, s31
	v_lshl_add_u64 v[24:25], s[22:23], 2, v[28:29]
	global_load_dwordx4 v[24:27], v[24:25], off nt
	s_and_b64 vcc, exec, s[0:1]
	s_cbranch_vccnz .LBB0_126
	s_lshl_b64 s[22:23], s[20:21], 2
	s_add_u32 s22, s18, s22
	s_addc_u32 s23, s19, s23
	global_load_dword v82, v35, s[22:23] offset:24
.LBB0_126:
	s_or_b32 s22, s20, 7
	s_mul_hi_u32 s23, s22, s31
	s_add_i32 s23, s23, s24
	s_mul_i32 s22, s22, s31
	v_lshl_add_u64 v[28:29], s[22:23], 2, v[28:29]
	global_load_dwordx4 v[28:31], v[28:29], off nt
	s_and_b64 vcc, exec, s[0:1]
	s_cbranch_vccnz .LBB0_65
	s_lshl_b64 s[0:1], s[20:21], 2
	s_add_u32 s0, s18, s0
	s_addc_u32 s1, s19, s1
	global_load_dword v84, v35, s[0:1] offset:28
	s_branch .LBB0_65
